# v37 + late weight transposes (w_branch_a/b, w_out, w_up, w_down) moved from P0 into P3 queue as hand-written 64x64 items
# baseline (speedup 1.0000x reference)
_Z13nsa_block_fwd4Args:
	s_load_dwordx2 s[86:87], s[0:1], 0x98
	v_writelane_b32 v248, s0, 14
	v_writelane_b32 v248, s1, 15
	s_mov_b32 s79, s2
	s_add_u32 s2, s0, 0x98
	s_addc_u32 s3, s1, 0
	v_and_b32_e32 v202, 0x3ff, v0
	s_waitcnt lgkmcnt(0)
	s_and_b32 s4, s86, 7
	v_readfirstlane_b32 s20, v202
	s_cmp_lg_u32 s4, 0
	s_mov_b32 s82, s79
	s_cbranch_scc1 .LBB0_2
	s_ashr_i32 s5, s79, 31
	s_lshr_b32 s5, s5, 29
	s_add_i32 s5, s79, s5
	s_and_b32 s6, s5, -8
	s_ashr_i32 s4, s86, 3
	s_sub_i32 s6, s79, s6
	s_mul_i32 s4, s4, s6
	s_ashr_i32 s5, s5, 3
	s_add_i32 s82, s4, s5

.LBB0_31:
	s_cmp_lg_u32 s86, 0x100
	s_cbranch_scc1 .Lp0_keep
	s_cmpk_lt_u32 s57, 0xc90
	s_cbranch_scc1 .Lp0_keep
	s_cmpk_lt_u32 s57, 0x2190
	s_cbranch_scc1 .LBB0_30

.LBB0_502:
	s_or_b64 exec, exec, s[0:1]
	v_readlane_b32 s0, v249, 51
	s_waitcnt lgkmcnt(0)
	s_barrier
	v_mov_b32_e32 v0, s0
	ds_read_b32 v0, v0
	s_movk_i32 s0, 0x400
	s_cmp_eq_u32 s88, 0x100
	s_cselect_b32 s0, 0x600, s0
	s_waitcnt lgkmcnt(0)
	s_barrier
	v_cmp_gt_i32_e32 vcc, s0, v0
	v_readfirstlane_b32 s6, v0
	s_cbranch_vccz .LBB0_746

.LBB0_507:
	s_or_b64 exec, exec, s[0:1]
	s_cmp_lg_u32 s88, 0x100
	s_cbranch_scc1 .Lp3_attn
	s_mul_hi_u32 s0, s6, 0xaaaaaaab
	s_lshr_b32 s0, s0, 2
	s_mul_i32 s1, s0, 6
	s_sub_i32 s1, s6, s1
	s_cmp_eq_u32 s1, 4
	s_cbranch_scc1 .Lp3_conv
	s_cmp_eq_u32 s1, 5
	s_cbranch_scc1 .Lp3_lw
	s_lshl_b32 s0, s0, 2
	s_add_i32 s6, s0, s1

.Lp3_lw:
	v_readfirstlane_b32 s1, v202
	v_mov_b32_e32 v200, v164
	s_lshr_b32 s1, s1, 6
	v_readlane_b32 s2, v248, 14
	v_readlane_b32 s3, v248, 15
	v_readlane_b32 s8, v249, 3
	v_readlane_b32 s9, v249, 4
	v_and_b32_e32 v2, 63, v202
	v_lshlrev_b32_e32 v3, 2, v2
	s_load_dwordx8 s[40:47], s[2:3], 0x50
	s_load_dwordx4 s[48:51], s[2:3], 0x70
	s_mul_i32 s20, s0, 21
	s_add_i32 s21, s20, 21
	s_lshr_b32 s20, s20, 1
	s_lshr_b32 s21, s21, 1
	s_sub_i32 s21, s21, s20
	s_waitcnt lgkmcnt(0)
	s_add_i32 s23, s20, s1
	s_cmpk_lt_u32 s23, 0x80
	s_cbranch_scc1 .Llw0_A
	s_cmpk_lt_u32 s23, 0x180
	s_cbranch_scc1 .Llw0_B
	s_cmpk_lt_u32 s23, 0x280
	s_cbranch_scc1 .Llw0_O
	s_cmpk_lt_u32 s23, 0x680
	s_cbranch_scc1 .Llw0_U
.Llw0_D:
	s_sub_u32 s10, s23, 0x680
	s_lshr_b32 s11, s10, 4
	s_and_b32 s12, s10, 0xf
	s_lshl_b32 s13, s11, 18
	s_lshl_b32 s14, s12, 8
	s_add_u32 s24, s50, s13
	s_addc_u32 s25, s51, 0
	s_add_u32 s24, s24, s14
	s_addc_u32 s25, s25, 0
	s_mov_b32 s26, 0x1000
	s_mul_i32 s15, s12, 0x80000
	s_lshl_b32 s16, s11, 7
	s_add_u32 s28, s8, 0x1c00000
	s_addc_u32 s29, s9, 0
	s_add_u32 s28, s28, s15
	s_addc_u32 s29, s29, 0
	s_add_u32 s28, s28, s16
	s_addc_u32 s29, s29, 0
	s_movk_i32 s30, 0x2000
	s_mov_b32 s31, 0
	s_branch .Llw0_go
.Llw0_A:
	s_mov_b32 s10, s23
	s_lshr_b32 s11, s10, 4
	s_and_b32 s12, s10, 0xf
	s_lshl_b32 s13, s11, 18
	s_lshl_b32 s14, s12, 8
	s_add_u32 s24, s40, s13
	s_addc_u32 s25, s41, 0
	s_add_u32 s24, s24, s14
	s_addc_u32 s25, s25, 0
	s_mov_b32 s26, 0x1000
	s_mul_i32 s15, s12, 0x30000
	s_lshl_b32 s16, s11, 7
	s_add_u32 s28, s8, 0xf00000
	s_addc_u32 s29, s9, 0
	s_add_u32 s28, s28, s15
	s_addc_u32 s29, s29, 0
	s_add_u32 s28, s28, s16
	s_addc_u32 s29, s29, 0
	s_movk_i32 s30, 0xc00
	s_mov_b32 s31, 0
	s_branch .Llw0_go
.Llw0_B:
	s_sub_u32 s10, s23, 0x80
	s_lshr_b32 s11, s10, 4
	s_and_b32 s12, s10, 0xf
	s_lshl_b32 s13, s11, 18
	s_lshl_b32 s14, s12, 8
	s_add_u32 s24, s42, s13
	s_addc_u32 s25, s43, 0
	s_add_u32 s24, s24, s14
	s_addc_u32 s25, s25, 0
	s_mov_b32 s26, 0x1000
	s_mul_i32 s15, s12, 0x30000
	s_lshl_b32 s16, s11, 7
	s_add_u32 s28, s8, 0xf00400
	s_addc_u32 s29, s9, 0
	s_add_u32 s28, s28, s15
	s_addc_u32 s29, s29, 0
	s_add_u32 s28, s28, s16
	s_addc_u32 s29, s29, 0
	s_movk_i32 s30, 0xc00
	s_mov_b32 s31, 0
	s_branch .Llw0_go
.Llw0_O:
	s_sub_u32 s10, s23, 0x180
	s_lshr_b32 s11, s10, 4
	s_and_b32 s12, s10, 0xf
	s_lshl_b32 s13, s11, 18
	s_lshl_b32 s14, s12, 8
	s_add_u32 s24, s44, s13
	s_addc_u32 s25, s45, 0
	s_add_u32 s24, s24, s14
	s_addc_u32 s25, s25, 0
	s_mov_b32 s26, 0x1000
	s_mul_i32 s15, s12, 0x20000
	s_lshl_b32 s16, s11, 7
	s_add_u32 s28, s8, 0x1200000
	s_addc_u32 s29, s9, 0
	s_add_u32 s28, s28, s15
	s_addc_u32 s29, s29, 0
	s_add_u32 s28, s28, s16
	s_addc_u32 s29, s29, 0
	s_movk_i32 s30, 0x800
	s_mov_b32 s31, 0
	s_branch .Llw0_go
.Llw0_U:
	s_sub_u32 s10, s23, 0x280
	s_lshr_b32 s11, s10, 6
	s_and_b32 s12, s10, 0x3f
	s_lshl_b32 s13, s11, 20
	s_lshl_b32 s14, s12, 8
	s_add_u32 s24, s48, s13
	s_addc_u32 s25, s49, 0
	s_add_u32 s24, s24, s14
	s_addc_u32 s25, s25, 0
	s_mov_b32 s26, 0x4000
	s_mul_i32 s15, s12, 0x20000
	s_lshl_b32 s16, s11, 7
	s_add_u32 s28, s8, 0x1400000
	s_addc_u32 s29, s9, 0
	s_add_u32 s28, s28, s15
	s_addc_u32 s29, s29, 0
	s_add_u32 s28, s28, s16
	s_addc_u32 s29, s29, 0
	s_movk_i32 s30, 0x800
	s_mov_b32 s31, 1
	s_lshl_b32 s17, s11, 8
	s_add_u32 s4, s46, s17
	s_addc_u32 s5, s47, 0
	s_branch .Llw0_go
.Llw0_go:
	v_mul_lo_u32 v4, v2, s30
	s_mov_b64 s[18:19], s[24:25]
	global_load_dword v8, v3, s[18:19]
	s_add_u32 s18, s18, s26
	s_addc_u32 s19, s19, 0
	global_load_dword v9, v3, s[18:19]
	s_add_u32 s18, s18, s26
	s_addc_u32 s19, s19, 0
	global_load_dword v10, v3, s[18:19]
	s_add_u32 s18, s18, s26
	s_addc_u32 s19, s19, 0
	global_load_dword v11, v3, s[18:19]
	s_add_u32 s18, s18, s26
	s_addc_u32 s19, s19, 0
	global_load_dword v12, v3, s[18:19]
	s_add_u32 s18, s18, s26
	s_addc_u32 s19, s19, 0
	global_load_dword v13, v3, s[18:19]
	s_add_u32 s18, s18, s26
	s_addc_u32 s19, s19, 0
	global_load_dword v14, v3, s[18:19]
	s_add_u32 s18, s18, s26
	s_addc_u32 s19, s19, 0
	global_load_dword v15, v3, s[18:19]
	s_add_u32 s18, s18, s26
	s_addc_u32 s19, s19, 0
	global_load_dword v16, v3, s[18:19]
	s_add_u32 s18, s18, s26
	s_addc_u32 s19, s19, 0
	global_load_dword v17, v3, s[18:19]
	s_add_u32 s18, s18, s26
	s_addc_u32 s19, s19, 0
	global_load_dword v18, v3, s[18:19]
	s_add_u32 s18, s18, s26
	s_addc_u32 s19, s19, 0
	global_load_dword v19, v3, s[18:19]
	s_add_u32 s18, s18, s26
	s_addc_u32 s19, s19, 0
	global_load_dword v20, v3, s[18:19]
	s_add_u32 s18, s18, s26
	s_addc_u32 s19, s19, 0
	global_load_dword v21, v3, s[18:19]
	s_add_u32 s18, s18, s26
	s_addc_u32 s19, s19, 0
	global_load_dword v22, v3, s[18:19]
	s_add_u32 s18, s18, s26
	s_addc_u32 s19, s19, 0
	global_load_dword v23, v3, s[18:19]
	s_add_u32 s18, s18, s26
	s_addc_u32 s19, s19, 0
	global_load_dword v24, v3, s[18:19]
	s_add_u32 s18, s18, s26
	s_addc_u32 s19, s19, 0
	global_load_dword v25, v3, s[18:19]
	s_add_u32 s18, s18, s26
	s_addc_u32 s19, s19, 0
	global_load_dword v26, v3, s[18:19]
	s_add_u32 s18, s18, s26
	s_addc_u32 s19, s19, 0
	global_load_dword v27, v3, s[18:19]
	s_add_u32 s18, s18, s26
	s_addc_u32 s19, s19, 0
	global_load_dword v28, v3, s[18:19]
	s_add_u32 s18, s18, s26
	s_addc_u32 s19, s19, 0
	global_load_dword v29, v3, s[18:19]
	s_add_u32 s18, s18, s26
	s_addc_u32 s19, s19, 0
	global_load_dword v30, v3, s[18:19]
	s_add_u32 s18, s18, s26
	s_addc_u32 s19, s19, 0
	global_load_dword v31, v3, s[18:19]
	s_add_u32 s18, s18, s26
	s_addc_u32 s19, s19, 0
	global_load_dword v32, v3, s[18:19]
	s_add_u32 s18, s18, s26
	s_addc_u32 s19, s19, 0
	global_load_dword v33, v3, s[18:19]
	s_add_u32 s18, s18, s26
	s_addc_u32 s19, s19, 0
	global_load_dword v34, v3, s[18:19]
	s_add_u32 s18, s18, s26
	s_addc_u32 s19, s19, 0
	global_load_dword v35, v3, s[18:19]
	s_add_u32 s18, s18, s26
	s_addc_u32 s19, s19, 0
	global_load_dword v36, v3, s[18:19]
	s_add_u32 s18, s18, s26
	s_addc_u32 s19, s19, 0
	global_load_dword v37, v3, s[18:19]
	s_add_u32 s18, s18, s26
	s_addc_u32 s19, s19, 0
	global_load_dword v38, v3, s[18:19]
	s_add_u32 s18, s18, s26
	s_addc_u32 s19, s19, 0
	global_load_dword v39, v3, s[18:19]
	s_add_u32 s18, s18, s26
	s_addc_u32 s19, s19, 0
	global_load_dword v40, v3, s[18:19]
	s_add_u32 s18, s18, s26
	s_addc_u32 s19, s19, 0
	global_load_dword v41, v3, s[18:19]
	s_add_u32 s18, s18, s26
	s_addc_u32 s19, s19, 0
	global_load_dword v42, v3, s[18:19]
	s_add_u32 s18, s18, s26
	s_addc_u32 s19, s19, 0
	global_load_dword v43, v3, s[18:19]
	s_add_u32 s18, s18, s26
	s_addc_u32 s19, s19, 0
	global_load_dword v44, v3, s[18:19]
	s_add_u32 s18, s18, s26
	s_addc_u32 s19, s19, 0
	global_load_dword v45, v3, s[18:19]
	s_add_u32 s18, s18, s26
	s_addc_u32 s19, s19, 0
	global_load_dword v46, v3, s[18:19]
	s_add_u32 s18, s18, s26
	s_addc_u32 s19, s19, 0
	global_load_dword v47, v3, s[18:19]
	s_add_u32 s18, s18, s26
	s_addc_u32 s19, s19, 0
	global_load_dword v48, v3, s[18:19]
	s_add_u32 s18, s18, s26
	s_addc_u32 s19, s19, 0
	global_load_dword v49, v3, s[18:19]
	s_add_u32 s18, s18, s26
	s_addc_u32 s19, s19, 0
	global_load_dword v50, v3, s[18:19]
	s_add_u32 s18, s18, s26
	s_addc_u32 s19, s19, 0
	global_load_dword v51, v3, s[18:19]
	s_add_u32 s18, s18, s26
	s_addc_u32 s19, s19, 0
	global_load_dword v52, v3, s[18:19]
	s_add_u32 s18, s18, s26
	s_addc_u32 s19, s19, 0
	global_load_dword v53, v3, s[18:19]
	s_add_u32 s18, s18, s26
	s_addc_u32 s19, s19, 0
	global_load_dword v54, v3, s[18:19]
	s_add_u32 s18, s18, s26
	s_addc_u32 s19, s19, 0
	global_load_dword v55, v3, s[18:19]
	s_add_u32 s18, s18, s26
	s_addc_u32 s19, s19, 0
	global_load_dword v56, v3, s[18:19]
	s_add_u32 s18, s18, s26
	s_addc_u32 s19, s19, 0
	global_load_dword v57, v3, s[18:19]
	s_add_u32 s18, s18, s26
	s_addc_u32 s19, s19, 0
	global_load_dword v58, v3, s[18:19]
	s_add_u32 s18, s18, s26
	s_addc_u32 s19, s19, 0
	global_load_dword v59, v3, s[18:19]
	s_add_u32 s18, s18, s26
	s_addc_u32 s19, s19, 0
	global_load_dword v60, v3, s[18:19]
	s_add_u32 s18, s18, s26
	s_addc_u32 s19, s19, 0
	global_load_dword v61, v3, s[18:19]
	s_add_u32 s18, s18, s26
	s_addc_u32 s19, s19, 0
	global_load_dword v62, v3, s[18:19]
	s_add_u32 s18, s18, s26
	s_addc_u32 s19, s19, 0
	global_load_dword v63, v3, s[18:19]
	s_add_u32 s18, s18, s26
	s_addc_u32 s19, s19, 0
	global_load_dword v64, v3, s[18:19]
	s_add_u32 s18, s18, s26
	s_addc_u32 s19, s19, 0
	global_load_dword v65, v3, s[18:19]
	s_add_u32 s18, s18, s26
	s_addc_u32 s19, s19, 0
	global_load_dword v66, v3, s[18:19]
	s_add_u32 s18, s18, s26
	s_addc_u32 s19, s19, 0
	global_load_dword v67, v3, s[18:19]
	s_add_u32 s18, s18, s26
	s_addc_u32 s19, s19, 0
	global_load_dword v68, v3, s[18:19]
	s_add_u32 s18, s18, s26
	s_addc_u32 s19, s19, 0
	global_load_dword v69, v3, s[18:19]
	s_add_u32 s18, s18, s26
	s_addc_u32 s19, s19, 0
	global_load_dword v70, v3, s[18:19]
	s_add_u32 s18, s18, s26
	s_addc_u32 s19, s19, 0
	global_load_dword v71, v3, s[18:19]
	s_cmp_eq_u32 s31, 0
	s_cbranch_scc1 .Llw0_nok
	s_load_dwordx16 s[52:67], s[4:5], 0x0
	s_waitcnt vmcnt(0) lgkmcnt(0)
	v_mul_f32_e32 v8, s52, v8
	v_mul_f32_e32 v9, s53, v9
	v_mul_f32_e32 v10, s54, v10
	v_mul_f32_e32 v11, s55, v11
	v_mul_f32_e32 v12, s56, v12
	v_mul_f32_e32 v13, s57, v13
	v_mul_f32_e32 v14, s58, v14
	v_mul_f32_e32 v15, s59, v15
	v_mul_f32_e32 v16, s60, v16
	v_mul_f32_e32 v17, s61, v17
	v_mul_f32_e32 v18, s62, v18
	v_mul_f32_e32 v19, s63, v19
	v_mul_f32_e32 v20, s64, v20
	v_mul_f32_e32 v21, s65, v21
	v_mul_f32_e32 v22, s66, v22
	v_mul_f32_e32 v23, s67, v23
	s_load_dwordx16 s[52:67], s[4:5], 0x40
	s_waitcnt vmcnt(0) lgkmcnt(0)
	v_mul_f32_e32 v24, s52, v24
	v_mul_f32_e32 v25, s53, v25
	v_mul_f32_e32 v26, s54, v26
	v_mul_f32_e32 v27, s55, v27
	v_mul_f32_e32 v28, s56, v28
	v_mul_f32_e32 v29, s57, v29
	v_mul_f32_e32 v30, s58, v30
	v_mul_f32_e32 v31, s59, v31
	v_mul_f32_e32 v32, s60, v32
	v_mul_f32_e32 v33, s61, v33
	v_mul_f32_e32 v34, s62, v34
	v_mul_f32_e32 v35, s63, v35
	v_mul_f32_e32 v36, s64, v36
	v_mul_f32_e32 v37, s65, v37
	v_mul_f32_e32 v38, s66, v38
	v_mul_f32_e32 v39, s67, v39
	s_load_dwordx16 s[52:67], s[4:5], 0x80
	s_waitcnt vmcnt(0) lgkmcnt(0)
	v_mul_f32_e32 v40, s52, v40
	v_mul_f32_e32 v41, s53, v41
	v_mul_f32_e32 v42, s54, v42
	v_mul_f32_e32 v43, s55, v43
	v_mul_f32_e32 v44, s56, v44
	v_mul_f32_e32 v45, s57, v45
	v_mul_f32_e32 v46, s58, v46
	v_mul_f32_e32 v47, s59, v47
	v_mul_f32_e32 v48, s60, v48
	v_mul_f32_e32 v49, s61, v49
	v_mul_f32_e32 v50, s62, v50
	v_mul_f32_e32 v51, s63, v51
	v_mul_f32_e32 v52, s64, v52
	v_mul_f32_e32 v53, s65, v53
	v_mul_f32_e32 v54, s66, v54
	v_mul_f32_e32 v55, s67, v55
	s_load_dwordx16 s[52:67], s[4:5], 0xc0
	s_waitcnt vmcnt(0) lgkmcnt(0)
	v_mul_f32_e32 v56, s52, v56
	v_mul_f32_e32 v57, s53, v57
	v_mul_f32_e32 v58, s54, v58
	v_mul_f32_e32 v59, s55, v59
	v_mul_f32_e32 v60, s56, v60
	v_mul_f32_e32 v61, s57, v61
	v_mul_f32_e32 v62, s58, v62
	v_mul_f32_e32 v63, s59, v63
	v_mul_f32_e32 v64, s60, v64
	v_mul_f32_e32 v65, s61, v65
	v_mul_f32_e32 v66, s62, v66
	v_mul_f32_e32 v67, s63, v67
	v_mul_f32_e32 v68, s64, v68
	v_mul_f32_e32 v69, s65, v69
	v_mul_f32_e32 v70, s66, v70
	v_mul_f32_e32 v71, s67, v71
.Llw0_nok:
	s_waitcnt vmcnt(0)
	v_cvt_pk_bf16_f32 v72, v8, v9
	v_cvt_pk_bf16_f32 v73, v10, v11
	v_cvt_pk_bf16_f32 v74, v12, v13
	v_cvt_pk_bf16_f32 v75, v14, v15
	v_cvt_pk_bf16_f32 v76, v16, v17
	v_cvt_pk_bf16_f32 v77, v18, v19
	v_cvt_pk_bf16_f32 v78, v20, v21
	v_cvt_pk_bf16_f32 v79, v22, v23
	v_cvt_pk_bf16_f32 v80, v24, v25
	v_cvt_pk_bf16_f32 v81, v26, v27
	v_cvt_pk_bf16_f32 v82, v28, v29
	v_cvt_pk_bf16_f32 v83, v30, v31
	v_cvt_pk_bf16_f32 v84, v32, v33
	v_cvt_pk_bf16_f32 v85, v34, v35
	v_cvt_pk_bf16_f32 v86, v36, v37
	v_cvt_pk_bf16_f32 v87, v38, v39
	v_cvt_pk_bf16_f32 v88, v40, v41
	v_cvt_pk_bf16_f32 v89, v42, v43
	v_cvt_pk_bf16_f32 v90, v44, v45
	v_cvt_pk_bf16_f32 v91, v46, v47
	v_cvt_pk_bf16_f32 v92, v48, v49
	v_cvt_pk_bf16_f32 v93, v50, v51
	v_cvt_pk_bf16_f32 v94, v52, v53
	v_cvt_pk_bf16_f32 v95, v54, v55
	v_cvt_pk_bf16_f32 v96, v56, v57
	v_cvt_pk_bf16_f32 v97, v58, v59
	v_cvt_pk_bf16_f32 v98, v60, v61
	v_cvt_pk_bf16_f32 v99, v62, v63
	v_cvt_pk_bf16_f32 v100, v64, v65
	v_cvt_pk_bf16_f32 v101, v66, v67
	v_cvt_pk_bf16_f32 v102, v68, v69
	v_cvt_pk_bf16_f32 v103, v70, v71
	global_store_dwordx4 v4, v[72:75], s[28:29]
	global_store_dwordx4 v4, v[76:79], s[28:29] offset:16
	global_store_dwordx4 v4, v[80:83], s[28:29] offset:32
	global_store_dwordx4 v4, v[84:87], s[28:29] offset:48
	global_store_dwordx4 v4, v[88:91], s[28:29] offset:64
	global_store_dwordx4 v4, v[92:95], s[28:29] offset:80
	global_store_dwordx4 v4, v[96:99], s[28:29] offset:96
	global_store_dwordx4 v4, v[100:103], s[28:29] offset:112
	s_add_i32 s22, s1, 8
	s_cmp_ge_u32 s22, s21
	s_cbranch_scc1 .Llw_done
	s_add_i32 s23, s20, s22
	s_cmpk_lt_u32 s23, 0x80
	s_cbranch_scc1 .Llw1_A
	s_cmpk_lt_u32 s23, 0x180
	s_cbranch_scc1 .Llw1_B
	s_cmpk_lt_u32 s23, 0x280
	s_cbranch_scc1 .Llw1_O
	s_cmpk_lt_u32 s23, 0x680
	s_cbranch_scc1 .Llw1_U

.Llw1_nok:
	s_waitcnt vmcnt(0)
	v_cvt_pk_bf16_f32 v72, v8, v9
	v_cvt_pk_bf16_f32 v73, v10, v11
	v_cvt_pk_bf16_f32 v74, v12, v13
	v_cvt_pk_bf16_f32 v75, v14, v15
	v_cvt_pk_bf16_f32 v76, v16, v17
	v_cvt_pk_bf16_f32 v77, v18, v19
	v_cvt_pk_bf16_f32 v78, v20, v21
	v_cvt_pk_bf16_f32 v79, v22, v23
	v_cvt_pk_bf16_f32 v80, v24, v25
	v_cvt_pk_bf16_f32 v81, v26, v27
	v_cvt_pk_bf16_f32 v82, v28, v29
	v_cvt_pk_bf16_f32 v83, v30, v31
	v_cvt_pk_bf16_f32 v84, v32, v33
	v_cvt_pk_bf16_f32 v85, v34, v35
	v_cvt_pk_bf16_f32 v86, v36, v37
	v_cvt_pk_bf16_f32 v87, v38, v39
	v_cvt_pk_bf16_f32 v88, v40, v41
	v_cvt_pk_bf16_f32 v89, v42, v43
	v_cvt_pk_bf16_f32 v90, v44, v45
	v_cvt_pk_bf16_f32 v91, v46, v47
	v_cvt_pk_bf16_f32 v92, v48, v49
	v_cvt_pk_bf16_f32 v93, v50, v51
	v_cvt_pk_bf16_f32 v94, v52, v53
	v_cvt_pk_bf16_f32 v95, v54, v55
	v_cvt_pk_bf16_f32 v96, v56, v57
	v_cvt_pk_bf16_f32 v97, v58, v59
	v_cvt_pk_bf16_f32 v98, v60, v61
	v_cvt_pk_bf16_f32 v99, v62, v63
	v_cvt_pk_bf16_f32 v100, v64, v65
	v_cvt_pk_bf16_f32 v101, v66, v67
	v_cvt_pk_bf16_f32 v102, v68, v69
	v_cvt_pk_bf16_f32 v103, v70, v71
	global_store_dwordx4 v4, v[72:75], s[28:29]
	global_store_dwordx4 v4, v[76:79], s[28:29] offset:16
	global_store_dwordx4 v4, v[80:83], s[28:29] offset:32
	global_store_dwordx4 v4, v[84:87], s[28:29] offset:48
	global_store_dwordx4 v4, v[88:91], s[28:29] offset:64
	global_store_dwordx4 v4, v[92:95], s[28:29] offset:80
	global_store_dwordx4 v4, v[96:99], s[28:29] offset:96
	global_store_dwordx4 v4, v[100:103], s[28:29] offset:112
.Llw_done:
	v_mov_b32_e32 v164, v200
	v_mbcnt_hi_u32_b32 v155, -1, v194
	v_and_b32_e32 v0, 64, v155
	v_mov_b32_e32 v154, 0x358637bd
	v_xor_b32_e32 v156, 32, v155
	v_add_u32_e32 v157, 64, v0
	v_mov_b32_e32 v158, 0xf149f2ca
	v_mov_b32_e32 v159, 0x7149f2ca
	v_mov_b32_e32 v160, 0x2080
	v_mov_b32_e32 v161, 0x461c4000
	v_mov_b32_e32 v162, 0xffffff80
	v_mov_b32_e32 v163, 0x63
	s_branch .Lp3_item_end
